# P8 epilogue: batch the 8 serialized rowmx atomic-loads into one group
# speedup vs baseline: 1.0029x; 1.0029x over previous
.LBB0_633:
	s_waitcnt lgkmcnt(1)
	v_lshlrev_b64 v[40:41], 2, v[188:189]
	v_lshl_add_u64 v[86:87], s[38:39], 0, v[40:41]
	global_load_dword v91, v[86:87], off sc1
	global_load_dword v90, v[86:87], off offset:64 sc1
	global_load_dword v85, v[86:87], off offset:128 sc1
	global_load_dword v84, v[86:87], off offset:192 sc1
	global_load_dword v83, v[86:87], off offset:512 sc1
	global_load_dword v82, v[86:87], off offset:576 sc1
	s_waitcnt lgkmcnt(0)
	global_load_dword v81, v[86:87], off offset:640 sc1
	global_load_dword v80, v[86:87], off offset:704 sc1
	s_lshl_b64 s[2:3], s[64:65], 2
	s_add_u32 s2, s91, s2
	s_addc_u32 s3, s92, s3
	v_lshl_add_u64 v[40:41], s[40:41], 0, v[40:41]
	global_load_dword v88, v161, s[2:3]
	global_load_dword v89, v[40:41], off sc1
	global_load_dword v236, v[40:41], off offset:64 sc1
	global_load_dword v237, v[40:41], off offset:128 sc1
	global_load_dword v238, v[40:41], off offset:192 sc1
	global_load_dword v239, v[40:41], off offset:512 sc1
	global_load_dword v240, v[40:41], off offset:576 sc1
	global_load_dword v241, v[40:41], off offset:640 sc1
	global_load_dword v242, v[40:41], off offset:704 sc1
	s_waitcnt vmcnt(15)
	v_pk_fma_f32 v[86:87], v[90:91], s[54:55], v[172:173] op_sel_hi:[1,0,0]
	s_nop 0
	v_mul_f32_e32 v90, 0x4b800000, v87
	v_cmp_gt_f32_e64 s[2:3], s86, v87
	s_nop 1
	v_cndmask_b32_e64 v87, v87, v90, s[2:3]
	v_rsq_f32_e32 v87, v87
	v_or_b32_e32 v90, s14, v230
	v_cmp_eq_u32_e32 vcc, 0, v90
	v_cmp_gt_f32_e64 s[14:15], s86, v86
	v_mul_f32_e32 v90, 0x45800000, v87
	v_cndmask_b32_e64 v202, v87, v90, s[2:3]
	s_waitcnt vmcnt(0)
	v_mul_f32_e32 v87, v202, v89
	v_sub_f32_e32 v89, 1.0, v202
	v_max_f32_e32 v89, 0, v89
	v_fmac_f32_e32 v87, v88, v89
	s_and_saveexec_b64 s[2:3], vcc
	s_cbranch_execz .LBB0_635
	v_mul_f32_e32 v89, 0x3c010204, v87
	v_lshl_add_u64 v[90:91], v[188:189], 2, s[42:43]
	global_store_dword v[90:91], v89, off
.LBB0_635:
	s_or_b64 exec, exec, s[2:3]
	v_lshl_add_u64 v[90:91], v[198:199], 2, s[40:41]
	v_mov_b32_e32 v89, v236
	v_mul_f32_e32 v90, 0x4b800000, v86
	v_cndmask_b32_e64 v86, v86, v90, s[14:15]
	v_rsq_f32_e32 v86, v86
	s_nop 0
	v_mul_f32_e32 v90, 0x45800000, v86
	v_cndmask_b32_e64 v200, v86, v90, s[14:15]
	v_sub_f32_e32 v86, 1.0, v200
	v_max_f32_e32 v86, 0, v86
	v_mul_f32_e32 v89, v200, v89
	v_fmac_f32_e32 v89, v88, v86
	s_and_saveexec_b64 s[2:3], vcc
	s_cbranch_execz .LBB0_637
	v_mul_f32_e32 v86, 0x3c010204, v89
	v_lshl_add_u64 v[90:91], v[198:199], 2, s[42:43]
	global_store_dword v[90:91], v86, off
.LBB0_637:
	s_or_b64 exec, exec, s[2:3]
	v_lshl_add_u64 v[90:91], v[216:217], 2, s[40:41]
	v_mov_b32_e32 v86, v237
	v_pk_fma_f32 v[84:85], v[84:85], s[54:55], v[172:173] op_sel_hi:[1,0,0]
	s_nop 0
	v_mul_f32_e32 v90, 0x4b800000, v85
	v_cmp_gt_f32_e64 s[2:3], s86, v85
	v_cmp_gt_f32_e64 s[14:15], s86, v84
	s_nop 0
	v_cndmask_b32_e64 v85, v85, v90, s[2:3]
	v_rsq_f32_e32 v85, v85
	s_nop 0
	v_mul_f32_e32 v90, 0x45800000, v85
	v_cndmask_b32_e64 v92, v85, v90, s[2:3]
	v_sub_f32_e32 v90, 1.0, v92
	v_mul_f32_e32 v85, v92, v86
	v_max_f32_e32 v86, 0, v90
	v_fmac_f32_e32 v85, v88, v86
	s_and_saveexec_b64 s[2:3], vcc
	s_cbranch_execz .LBB0_639
	v_mul_f32_e32 v86, 0x3c010204, v85
	v_lshl_add_u64 v[90:91], v[216:217], 2, s[42:43]
	global_store_dword v[90:91], v86, off
.LBB0_639:
	s_or_b64 exec, exec, s[2:3]
	v_lshl_add_u64 v[90:91], v[218:219], 2, s[40:41]
	v_mov_b32_e32 v86, v238
	v_mul_f32_e32 v90, 0x4b800000, v84
	v_cndmask_b32_e64 v84, v84, v90, s[14:15]
	v_rsq_f32_e32 v84, v84
	s_nop 0
	v_mul_f32_e32 v90, 0x45800000, v84
	v_cndmask_b32_e64 v90, v84, v90, s[14:15]
	v_sub_f32_e32 v84, 1.0, v90
	v_max_f32_e32 v84, 0, v84
	v_mul_f32_e32 v91, v90, v86
	v_fmac_f32_e32 v91, v88, v84
	s_and_saveexec_b64 s[2:3], vcc
	s_cbranch_execz .LBB0_641
	v_mul_f32_e32 v84, 0x3c010204, v91
	v_lshl_add_u64 v[94:95], v[218:219], 2, s[42:43]
	global_store_dword v[94:95], v84, off
.LBB0_641:
	s_or_b64 exec, exec, s[2:3]
	v_mov_b32_e32 v84, v239
	v_pk_fma_f32 v[82:83], v[82:83], s[54:55], v[172:173] op_sel_hi:[1,0,0]
	s_nop 0
	v_mul_f32_e32 v86, 0x4b800000, v83
	v_cmp_gt_f32_e64 s[2:3], s86, v83
	v_cmp_gt_f32_e64 s[14:15], s86, v82
	s_nop 0
	v_cndmask_b32_e64 v83, v83, v86, s[2:3]
	v_rsq_f32_e32 v83, v83
	s_nop 0
	v_mul_f32_e32 v86, 0x45800000, v83
	v_cndmask_b32_e64 v86, v83, v86, s[2:3]
	v_sub_f32_e32 v83, 1.0, v86
	v_max_f32_e32 v83, 0, v83
	v_mul_f32_e32 v93, v86, v84
	v_fmac_f32_e32 v93, v88, v83
	s_and_saveexec_b64 s[2:3], vcc
	s_cbranch_execz .LBB0_643
	v_mul_f32_e32 v83, 0x3c010204, v93
	v_lshl_add_u64 v[94:95], v[220:221], 2, s[42:43]
	global_store_dword v[94:95], v83, off
.LBB0_643:
	s_or_b64 exec, exec, s[2:3]
	v_mov_b32_e32 v83, v240
	v_mul_f32_e32 v84, 0x4b800000, v82
	v_cndmask_b32_e64 v82, v82, v84, s[14:15]
	v_rsq_f32_e32 v82, v82
	s_nop 0
	v_mul_f32_e32 v84, 0x45800000, v82
	v_cndmask_b32_e64 v84, v82, v84, s[14:15]
	v_sub_f32_e32 v82, 1.0, v84
	v_max_f32_e32 v82, 0, v82
	v_mul_f32_e32 v94, v84, v83
	v_fmac_f32_e32 v94, v88, v82
	s_and_saveexec_b64 s[2:3], vcc
	s_cbranch_execz .LBB0_645
	v_mul_f32_e32 v95, 0x3c010204, v94
	v_lshl_add_u64 v[82:83], v[222:223], 2, s[42:43]
	global_store_dword v[82:83], v95, off
.LBB0_645:
	s_or_b64 exec, exec, s[2:3]
	v_mov_b32_e32 v95, v241
	v_pk_fma_f32 v[82:83], v[80:81], s[54:55], v[172:173] op_sel_hi:[1,0,0]
	s_nop 0
	v_mul_f32_e32 v80, 0x4b800000, v83
	v_cmp_gt_f32_e64 s[2:3], s86, v83
	v_cmp_gt_f32_e64 s[14:15], s86, v82
	s_nop 0
	v_cndmask_b32_e64 v80, v83, v80, s[2:3]
	v_rsq_f32_e32 v80, v80
	s_nop 0
	v_mul_f32_e32 v81, 0x45800000, v80
	v_cndmask_b32_e64 v80, v80, v81, s[2:3]
	v_sub_f32_e32 v83, 1.0, v80
	v_max_f32_e32 v83, 0, v83
	v_mul_f32_e32 v81, v80, v95
	v_fmac_f32_e32 v81, v88, v83
	s_and_saveexec_b64 s[2:3], vcc
	s_cbranch_execz .LBB0_647
	v_mul_f32_e32 v83, 0x3c010204, v81
	v_lshl_add_u64 v[198:199], v[224:225], 2, s[42:43]
	global_store_dword v[198:199], v83, off
.LBB0_647:
	s_or_b64 exec, exec, s[2:3]
	v_mov_b32_e32 v41, v242
	v_mul_f32_e32 v40, 0x4b800000, v82
	v_cndmask_b32_e64 v40, v82, v40, s[14:15]
	v_rsq_f32_e32 v40, v40
	s_nop 0
	v_mul_f32_e32 v82, 0x45800000, v40
	v_cndmask_b32_e64 v40, v40, v82, s[14:15]
	v_sub_f32_e32 v82, 1.0, v40
	v_max_f32_e32 v82, 0, v82
	v_mul_f32_e32 v41, v40, v41
	v_fmac_f32_e32 v41, v88, v82
	s_and_saveexec_b64 s[2:3], vcc
	s_cbranch_execz .LBB0_649
	v_mul_f32_e32 v82, 0x3c010204, v41
	v_lshl_add_u64 v[42:43], v[42:43], 2, s[42:43]
	global_store_dword v[42:43], v82, off
